# P2 depthwise-conv FMA block: 145 adjacent independent v_fmac pairs on aligned register pairs merged into v_pk_fma_f32
# baseline (speedup 1.0000x reference)
.LBB0_552:
	s_waitcnt lgkmcnt(14)
	v_lshlrev_b32_e32 v32, 16, v32
	v_lshlrev_b32_e32 v207, 16, v33
	v_lshlrev_b32_e32 v208, 16, v34
	v_lshlrev_b32_e32 v179, 16, v74
	s_waitcnt vmcnt(2)
	v_fma_f32 v32, v73, v32, v127
	v_fma_f32 v74, v73, v207, v127
	v_lshlrev_b32_e32 v209, 16, v35
	v_fmac_f32_e32 v32, v77, v207
	v_fmac_f32_e32 v74, v77, v208
	v_lshlrev_b32_e32 v210, 16, v36
	v_lshlrev_b32_e32 v164, 16, v86
	v_fma_f32 v86, v73, v208, v127
	v_fmac_f32_e32 v32, v98, v208
	v_fmac_f32_e32 v74, v98, v209
	v_lshlrev_b32_e32 v211, 16, v37
	v_lshlrev_b32_e32 v165, 16, v85
	v_fma_f32 v85, v73, v209, v127
	v_fmac_f32_e32 v86, v77, v209
	v_fmac_f32_e32 v32, v99, v209
	v_fmac_f32_e32 v74, v99, v210
	v_lshlrev_b32_e32 v212, 16, v38
	v_fma_f32 v35, v73, v210, v127
	v_fmac_f32_e32 v85, v77, v210
	v_fmac_f32_e32 v86, v98, v210
	v_fmac_f32_e32 v32, v100, v210
	v_fmac_f32_e32 v74, v100, v211
	v_lshlrev_b32_e32 v213, 16, v39
	v_fma_f32 v34, v73, v211, v127
	v_fmac_f32_e32 v35, v77, v211
	v_fmac_f32_e32 v85, v98, v211
	v_fmac_f32_e32 v86, v99, v211
	v_fmac_f32_e32 v32, v101, v211
	v_fmac_f32_e32 v74, v101, v212
	v_lshlrev_b32_e32 v193, 16, v40
	v_lshlrev_b32_e32 v166, 16, v84
	v_fma_f32 v84, v73, v212, v127
	v_fmac_f32_e32 v34, v77, v212
	v_fmac_f32_e32 v35, v98, v212
	v_fmac_f32_e32 v85, v99, v212
	v_fmac_f32_e32 v86, v100, v212
	v_fmac_f32_e32 v32, v102, v212
	v_fmac_f32_e32 v74, v102, v213
	v_lshlrev_b32_e32 v192, 16, v41
	v_lshlrev_b32_e32 v167, 16, v83
	v_fma_f32 v83, v73, v213, v127
	v_fmac_f32_e32 v84, v77, v213
	v_pk_fma_f32 v[34:35], v[98:99], v[212:213], v[34:35] op_sel:[0,1,0] op_sel_hi:[1,1,1]
	v_fmac_f32_e32 v85, v100, v213
	v_fmac_f32_e32 v86, v101, v213
	v_fmac_f32_e32 v32, v103, v213
	v_fmac_f32_e32 v74, v103, v193
	v_lshlrev_b32_e32 v191, 16, v42
	v_lshlrev_b32_e32 v168, 16, v82
	v_fma_f32 v82, v73, v193, v127
	v_fmac_f32_e32 v83, v77, v193
	v_fmac_f32_e32 v84, v98, v193
	v_fmac_f32_e32 v34, v99, v193
	v_fmac_f32_e32 v35, v100, v193
	v_fmac_f32_e32 v85, v101, v193
	v_fmac_f32_e32 v86, v102, v193
	v_fmac_f32_e32 v32, v104, v193
	v_fmac_f32_e32 v74, v104, v192
	v_lshlrev_b32_e32 v190, 16, v43
	v_lshlrev_b32_e32 v169, 16, v81
	v_fma_f32 v81, v73, v192, v127
	v_fmac_f32_e32 v82, v77, v192
	v_fmac_f32_e32 v83, v98, v192
	v_fmac_f32_e32 v84, v99, v192
	v_pk_fma_f32 v[34:35], v[100:101], v[192:193], v[34:35] op_sel_hi:[1,0,1]
	v_fmac_f32_e32 v85, v102, v192
	v_fmac_f32_e32 v86, v103, v192
	v_fmac_f32_e32 v32, v105, v192
	v_fmac_f32_e32 v74, v105, v191
	v_lshlrev_b32_e32 v189, 16, v44
	v_lshlrev_b32_e32 v170, 16, v80
	v_fma_f32 v80, v73, v191, v127
	v_fmac_f32_e32 v81, v77, v191
	v_pk_fma_f32 v[82:83], v[98:99], v[190:191], v[82:83] op_sel:[0,1,0] op_sel_hi:[1,1,1]
	v_fmac_f32_e32 v84, v100, v191
	v_fmac_f32_e32 v34, v101, v191
	v_fmac_f32_e32 v35, v102, v191
	v_fmac_f32_e32 v85, v103, v191
	v_fmac_f32_e32 v86, v104, v191
	v_fmac_f32_e32 v32, v106, v191
	v_fmac_f32_e32 v74, v106, v190
	v_lshlrev_b32_e32 v188, 16, v45
	v_lshlrev_b32_e32 v171, 16, v79
	v_fma_f32 v79, v73, v190, v127
	v_fmac_f32_e32 v80, v77, v190
	v_fmac_f32_e32 v81, v98, v190
	v_fmac_f32_e32 v82, v99, v190
	v_fmac_f32_e32 v83, v100, v190
	v_fmac_f32_e32 v84, v101, v190
	v_pk_fma_f32 v[34:35], v[102:103], v[190:191], v[34:35] op_sel_hi:[1,0,1]
	v_fmac_f32_e32 v85, v104, v190
	v_fmac_f32_e32 v86, v105, v190
	v_fmac_f32_e32 v32, v107, v190
	v_fmac_f32_e32 v74, v107, v189
	v_lshlrev_b32_e32 v187, 16, v46
	v_lshlrev_b32_e32 v173, 16, v76
	v_fma_f32 v76, v73, v189, v127
	v_fmac_f32_e32 v79, v77, v189
	v_pk_fma_f32 v[80:81], v[98:99], v[188:189], v[80:81] op_sel:[0,1,0] op_sel_hi:[1,1,1]
	v_pk_fma_f32 v[82:83], v[100:101], v[188:189], v[82:83] op_sel:[0,1,0] op_sel_hi:[1,1,1]
	v_fmac_f32_e32 v84, v102, v189
	v_fmac_f32_e32 v34, v103, v189
	v_fmac_f32_e32 v35, v104, v189
	v_fmac_f32_e32 v85, v105, v189
	v_fmac_f32_e32 v86, v106, v189
	v_fmac_f32_e32 v32, v108, v189
	v_fmac_f32_e32 v74, v108, v188
	v_lshlrev_b32_e32 v186, 16, v47
	v_lshlrev_b32_e32 v178, 16, v75
	v_fma_f32 v75, v73, v188, v127
	v_fmac_f32_e32 v76, v77, v188
	v_fmac_f32_e32 v79, v98, v188
	v_fmac_f32_e32 v80, v99, v188
	v_fmac_f32_e32 v81, v100, v188
	v_fmac_f32_e32 v82, v101, v188
	v_fmac_f32_e32 v83, v102, v188
	v_fmac_f32_e32 v84, v103, v188
	v_pk_fma_f32 v[34:35], v[104:105], v[188:189], v[34:35] op_sel_hi:[1,0,1]
	v_fmac_f32_e32 v85, v106, v188
	v_fmac_f32_e32 v86, v107, v188
	v_fmac_f32_e32 v32, v109, v188
	v_fmac_f32_e32 v74, v109, v187
	v_lshlrev_b32_e32 v185, 16, v48
	v_lshlrev_b32_e32 v180, 16, v72
	v_fma_f32 v72, v73, v187, v127
	v_fmac_f32_e32 v75, v77, v187
	v_fmac_f32_e32 v76, v98, v187
	v_fmac_f32_e32 v79, v99, v187
	v_pk_fma_f32 v[80:81], v[100:101], v[186:187], v[80:81] op_sel:[0,1,0] op_sel_hi:[1,1,1]
	v_pk_fma_f32 v[82:83], v[102:103], v[186:187], v[82:83] op_sel:[0,1,0] op_sel_hi:[1,1,1]
	v_fmac_f32_e32 v84, v104, v187
	v_fmac_f32_e32 v34, v105, v187
	v_fmac_f32_e32 v35, v106, v187
	v_fmac_f32_e32 v85, v107, v187
	v_fmac_f32_e32 v86, v108, v187
	v_fmac_f32_e32 v32, v110, v187
	v_fmac_f32_e32 v74, v110, v186
	v_lshlrev_b32_e32 v184, 16, v49
	v_lshlrev_b32_e32 v181, 16, v52
	v_fma_f32 v52, v73, v186, v127
	v_fmac_f32_e32 v72, v77, v186
	v_fmac_f32_e32 v75, v98, v186
	v_fmac_f32_e32 v76, v99, v186
	v_fmac_f32_e32 v79, v100, v186
	v_fmac_f32_e32 v80, v101, v186
	v_fmac_f32_e32 v81, v102, v186
	v_fmac_f32_e32 v82, v103, v186
	v_fmac_f32_e32 v83, v104, v186
	v_fmac_f32_e32 v84, v105, v186
	v_pk_fma_f32 v[34:35], v[106:107], v[186:187], v[34:35] op_sel_hi:[1,0,1]
	v_fmac_f32_e32 v85, v108, v186
	v_fmac_f32_e32 v86, v109, v186
	v_fmac_f32_e32 v32, v111, v186
	v_fmac_f32_e32 v74, v111, v185
	v_lshlrev_b32_e32 v183, 16, v50
	v_lshlrev_b32_e32 v182, 16, v51
	v_fma_f32 v51, v73, v185, v127
	v_fmac_f32_e32 v52, v77, v185
	v_fmac_f32_e32 v72, v98, v185
	v_fmac_f32_e32 v75, v99, v185
	v_fmac_f32_e32 v76, v100, v185
	v_fmac_f32_e32 v79, v101, v185
	v_pk_fma_f32 v[80:81], v[102:103], v[184:185], v[80:81] op_sel:[0,1,0] op_sel_hi:[1,1,1]
	v_pk_fma_f32 v[82:83], v[104:105], v[184:185], v[82:83] op_sel:[0,1,0] op_sel_hi:[1,1,1]
	v_fmac_f32_e32 v84, v106, v185
	v_fmac_f32_e32 v34, v107, v185
	v_fmac_f32_e32 v35, v108, v185
	v_fmac_f32_e32 v85, v109, v185
	v_fmac_f32_e32 v86, v110, v185
	v_fmac_f32_e32 v32, v112, v185
	v_fmac_f32_e32 v74, v112, v184
	v_fma_f32 v50, v73, v184, v127
	v_fmac_f32_e32 v51, v77, v184
	v_fmac_f32_e32 v52, v98, v184
	v_fmac_f32_e32 v72, v99, v184
	v_fmac_f32_e32 v75, v100, v184
	v_fmac_f32_e32 v76, v101, v184
	v_fmac_f32_e32 v79, v102, v184
	v_fmac_f32_e32 v80, v103, v184
	v_fmac_f32_e32 v81, v104, v184
	v_fmac_f32_e32 v82, v105, v184
	v_fmac_f32_e32 v83, v106, v184
	v_fmac_f32_e32 v84, v107, v184
	v_pk_fma_f32 v[34:35], v[108:109], v[184:185], v[34:35] op_sel_hi:[1,0,1]
	v_fmac_f32_e32 v85, v110, v184
	v_fmac_f32_e32 v86, v111, v184
	v_fmac_f32_e32 v32, v113, v184
	v_fmac_f32_e32 v74, v113, v183
	v_fma_f32 v49, v73, v183, v127
	v_fmac_f32_e32 v50, v77, v183
	v_fmac_f32_e32 v51, v98, v183
	v_fmac_f32_e32 v52, v99, v183
	v_fmac_f32_e32 v72, v100, v183
	v_fmac_f32_e32 v75, v101, v183
	v_fmac_f32_e32 v76, v102, v183
	v_fmac_f32_e32 v79, v103, v183
	v_pk_fma_f32 v[80:81], v[104:105], v[182:183], v[80:81] op_sel:[0,1,0] op_sel_hi:[1,1,1]
	v_pk_fma_f32 v[82:83], v[106:107], v[182:183], v[82:83] op_sel:[0,1,0] op_sel_hi:[1,1,1]
	v_fmac_f32_e32 v84, v108, v183
	v_fmac_f32_e32 v34, v109, v183
	v_fmac_f32_e32 v35, v110, v183
	v_fmac_f32_e32 v85, v111, v183
	v_fmac_f32_e32 v86, v112, v183
	v_fmac_f32_e32 v32, v114, v183
	v_fmac_f32_e32 v74, v114, v182
	v_fma_f32 v48, v73, v182, v127
	v_fmac_f32_e32 v49, v77, v182
	v_pk_fma_f32 v[50:51], v[98:99], v[182:183], v[50:51] op_sel_hi:[1,0,1]
	v_fmac_f32_e32 v52, v100, v182
	v_fmac_f32_e32 v72, v101, v182
	v_fmac_f32_e32 v75, v102, v182
	v_fmac_f32_e32 v76, v103, v182
	v_fmac_f32_e32 v79, v104, v182
	v_fmac_f32_e32 v80, v105, v182
	v_fmac_f32_e32 v81, v106, v182
	v_fmac_f32_e32 v82, v107, v182
	v_fmac_f32_e32 v83, v108, v182
	v_fmac_f32_e32 v84, v109, v182
	v_pk_fma_f32 v[34:35], v[110:111], v[182:183], v[34:35] op_sel_hi:[1,0,1]
	v_fmac_f32_e32 v85, v112, v182
	v_fmac_f32_e32 v86, v113, v182
	v_fmac_f32_e32 v32, v115, v182
	v_fmac_f32_e32 v74, v115, v181
	v_fma_f32 v47, v73, v181, v127
	v_fmac_f32_e32 v48, v77, v181
	v_fmac_f32_e32 v49, v98, v181
	v_fmac_f32_e32 v50, v99, v181
	v_fmac_f32_e32 v51, v100, v181
	v_fmac_f32_e32 v52, v101, v181
	v_fmac_f32_e32 v72, v102, v181
	v_fmac_f32_e32 v75, v103, v181
	v_fmac_f32_e32 v76, v104, v181
	v_fmac_f32_e32 v79, v105, v181
	v_pk_fma_f32 v[80:81], v[106:107], v[180:181], v[80:81] op_sel:[0,1,0] op_sel_hi:[1,1,1]
	v_pk_fma_f32 v[82:83], v[108:109], v[180:181], v[82:83] op_sel:[0,1,0] op_sel_hi:[1,1,1]
	v_fmac_f32_e32 v84, v110, v181
	v_fmac_f32_e32 v34, v111, v181
	v_fmac_f32_e32 v35, v112, v181
	v_fmac_f32_e32 v85, v113, v181
	v_fmac_f32_e32 v86, v114, v181
	v_fmac_f32_e32 v32, v116, v181
	v_fmac_f32_e32 v74, v116, v180
	v_fma_f32 v46, v73, v180, v127
	v_fmac_f32_e32 v47, v77, v180
	v_pk_fma_f32 v[48:49], v[98:99], v[180:181], v[48:49] op_sel_hi:[1,0,1]
	v_pk_fma_f32 v[50:51], v[100:101], v[180:181], v[50:51] op_sel_hi:[1,0,1]
	v_fmac_f32_e32 v52, v102, v180
	v_fmac_f32_e32 v72, v103, v180
	v_fmac_f32_e32 v75, v104, v180
	v_fmac_f32_e32 v76, v105, v180
	v_fmac_f32_e32 v79, v106, v180
	v_fmac_f32_e32 v80, v107, v180
	v_fmac_f32_e32 v81, v108, v180
	v_fmac_f32_e32 v82, v109, v180
	v_fmac_f32_e32 v83, v110, v180
	v_fmac_f32_e32 v84, v111, v180
	v_pk_fma_f32 v[34:35], v[112:113], v[180:181], v[34:35] op_sel_hi:[1,0,1]
	v_fmac_f32_e32 v85, v114, v180
	v_fmac_f32_e32 v86, v115, v180
	v_fmac_f32_e32 v32, v117, v180
	v_fmac_f32_e32 v74, v117, v179
	s_waitcnt lgkmcnt(5)
	v_lshlrev_b32_e32 v177, 16, v153
	v_fma_f32 v45, v73, v179, v127
	v_fmac_f32_e32 v46, v77, v179
	v_fmac_f32_e32 v47, v98, v179
	v_fmac_f32_e32 v48, v99, v179
	v_fmac_f32_e32 v49, v100, v179
	v_fmac_f32_e32 v50, v101, v179
	v_fmac_f32_e32 v51, v102, v179
	v_fmac_f32_e32 v52, v103, v179
	v_fmac_f32_e32 v72, v104, v179
	v_fmac_f32_e32 v75, v105, v179
	v_fmac_f32_e32 v76, v106, v179
	v_fmac_f32_e32 v79, v107, v179
	v_pk_fma_f32 v[80:81], v[108:109], v[178:179], v[80:81] op_sel:[0,1,0] op_sel_hi:[1,1,1]
	v_pk_fma_f32 v[82:83], v[110:111], v[178:179], v[82:83] op_sel:[0,1,0] op_sel_hi:[1,1,1]
	v_fmac_f32_e32 v84, v112, v179
	v_fmac_f32_e32 v34, v113, v179
	v_fmac_f32_e32 v35, v114, v179
	v_fmac_f32_e32 v85, v115, v179
	v_fmac_f32_e32 v86, v116, v179
	v_fmac_f32_e32 v32, v118, v179
	v_fmac_f32_e32 v74, v118, v178
	s_waitcnt lgkmcnt(4)
	v_lshlrev_b32_e32 v176, 16, v154
	v_fma_f32 v44, v73, v178, v127
	v_fmac_f32_e32 v45, v77, v178
	v_pk_fma_f32 v[46:47], v[98:99], v[178:179], v[46:47] op_sel_hi:[1,0,1]
	v_pk_fma_f32 v[48:49], v[100:101], v[178:179], v[48:49] op_sel_hi:[1,0,1]
	v_pk_fma_f32 v[50:51], v[102:103], v[178:179], v[50:51] op_sel_hi:[1,0,1]
	v_fmac_f32_e32 v52, v104, v178
	v_fmac_f32_e32 v72, v105, v178
	v_fmac_f32_e32 v75, v106, v178
	v_fmac_f32_e32 v76, v107, v178
	v_fmac_f32_e32 v79, v108, v178
	v_fmac_f32_e32 v80, v109, v178
	v_fmac_f32_e32 v81, v110, v178
	v_fmac_f32_e32 v82, v111, v178
	v_fmac_f32_e32 v83, v112, v178
	v_fmac_f32_e32 v84, v113, v178
	v_pk_fma_f32 v[34:35], v[114:115], v[178:179], v[34:35] op_sel_hi:[1,0,1]
	v_fmac_f32_e32 v85, v116, v178
	v_fmac_f32_e32 v86, v117, v178
	v_fmac_f32_e32 v32, v119, v178
	v_fmac_f32_e32 v74, v119, v177
	s_waitcnt lgkmcnt(3)
	v_lshlrev_b32_e32 v175, 16, v155
	v_fma_f32 v43, v73, v177, v127
	v_fmac_f32_e32 v44, v77, v177
	v_fmac_f32_e32 v45, v98, v177
	v_fmac_f32_e32 v46, v99, v177
	v_fmac_f32_e32 v47, v100, v177
	v_fmac_f32_e32 v48, v101, v177
	v_fmac_f32_e32 v49, v102, v177
	v_fmac_f32_e32 v50, v103, v177
	v_fmac_f32_e32 v51, v104, v177
	v_fmac_f32_e32 v52, v105, v177
	v_fmac_f32_e32 v72, v106, v177
	v_fmac_f32_e32 v75, v107, v177
	v_fmac_f32_e32 v76, v108, v177
	v_fmac_f32_e32 v79, v109, v177
	v_pk_fma_f32 v[80:81], v[110:111], v[176:177], v[80:81] op_sel:[0,1,0] op_sel_hi:[1,1,1]
	v_pk_fma_f32 v[82:83], v[112:113], v[176:177], v[82:83] op_sel:[0,1,0] op_sel_hi:[1,1,1]
	v_fmac_f32_e32 v84, v114, v177
	v_fmac_f32_e32 v34, v115, v177
	v_fmac_f32_e32 v35, v116, v177
	v_fmac_f32_e32 v85, v117, v177
	v_fmac_f32_e32 v86, v118, v177
	v_fmac_f32_e32 v32, v120, v177
	v_fmac_f32_e32 v74, v120, v176
	s_waitcnt lgkmcnt(2)
	v_lshlrev_b32_e32 v174, 16, v156
	v_fma_f32 v42, v73, v176, v127
	v_fmac_f32_e32 v43, v77, v176
	v_pk_fma_f32 v[44:45], v[98:99], v[176:177], v[44:45] op_sel_hi:[1,0,1]
	v_pk_fma_f32 v[46:47], v[100:101], v[176:177], v[46:47] op_sel_hi:[1,0,1]
	v_pk_fma_f32 v[48:49], v[102:103], v[176:177], v[48:49] op_sel_hi:[1,0,1]
	v_pk_fma_f32 v[50:51], v[104:105], v[176:177], v[50:51] op_sel_hi:[1,0,1]
	v_fmac_f32_e32 v52, v106, v176
	v_fmac_f32_e32 v72, v107, v176
	v_fmac_f32_e32 v75, v108, v176
	v_fmac_f32_e32 v76, v109, v176
	v_fmac_f32_e32 v79, v110, v176
	v_fmac_f32_e32 v80, v111, v176
	v_fmac_f32_e32 v81, v112, v176
	v_fmac_f32_e32 v82, v113, v176
	v_fmac_f32_e32 v83, v114, v176
	v_fmac_f32_e32 v84, v115, v176
	v_pk_fma_f32 v[34:35], v[116:117], v[176:177], v[34:35] op_sel_hi:[1,0,1]
	v_fmac_f32_e32 v85, v118, v176
	v_fmac_f32_e32 v86, v119, v176
	v_fmac_f32_e32 v32, v121, v176
	v_fmac_f32_e32 v74, v121, v175
	v_fma_f32 v41, v73, v175, v127
	v_fmac_f32_e32 v42, v77, v175
	v_fmac_f32_e32 v43, v98, v175
	v_fmac_f32_e32 v44, v99, v175
	v_fmac_f32_e32 v45, v100, v175
	v_fmac_f32_e32 v46, v101, v175
	v_fmac_f32_e32 v47, v102, v175
	v_fmac_f32_e32 v48, v103, v175
	v_fmac_f32_e32 v49, v104, v175
	v_fmac_f32_e32 v50, v105, v175
	v_fmac_f32_e32 v51, v106, v175
	v_fmac_f32_e32 v52, v107, v175
	v_fmac_f32_e32 v72, v108, v175
	v_fmac_f32_e32 v75, v109, v175
	v_fmac_f32_e32 v76, v110, v175
	v_fmac_f32_e32 v79, v111, v175
	v_pk_fma_f32 v[80:81], v[112:113], v[174:175], v[80:81] op_sel:[0,1,0] op_sel_hi:[1,1,1]
	v_pk_fma_f32 v[82:83], v[114:115], v[174:175], v[82:83] op_sel:[0,1,0] op_sel_hi:[1,1,1]
	v_fmac_f32_e32 v84, v116, v175
	v_fmac_f32_e32 v34, v117, v175
	v_fmac_f32_e32 v35, v118, v175
	v_fmac_f32_e32 v85, v119, v175
	v_fmac_f32_e32 v86, v120, v175
	v_fmac_f32_e32 v32, v122, v175
	v_fmac_f32_e32 v74, v122, v174
	v_lshlrev_b32_e32 v172, 16, v78
	v_fma_f32 v40, v73, v174, v127
	v_fmac_f32_e32 v41, v77, v174
	v_pk_fma_f32 v[42:43], v[98:99], v[174:175], v[42:43] op_sel_hi:[1,0,1]
	v_pk_fma_f32 v[44:45], v[100:101], v[174:175], v[44:45] op_sel_hi:[1,0,1]
	v_pk_fma_f32 v[46:47], v[102:103], v[174:175], v[46:47] op_sel_hi:[1,0,1]
	v_pk_fma_f32 v[48:49], v[104:105], v[174:175], v[48:49] op_sel_hi:[1,0,1]
	v_pk_fma_f32 v[50:51], v[106:107], v[174:175], v[50:51] op_sel_hi:[1,0,1]
	v_fmac_f32_e32 v52, v108, v174
	v_fmac_f32_e32 v72, v109, v174
	v_fmac_f32_e32 v75, v110, v174
	v_fmac_f32_e32 v76, v111, v174
	v_fmac_f32_e32 v79, v112, v174
	v_fmac_f32_e32 v80, v113, v174
	v_fmac_f32_e32 v81, v114, v174
	v_fmac_f32_e32 v82, v115, v174
	v_fmac_f32_e32 v83, v116, v174
	v_fmac_f32_e32 v84, v117, v174
	v_pk_fma_f32 v[34:35], v[118:119], v[174:175], v[34:35] op_sel_hi:[1,0,1]
	v_fmac_f32_e32 v85, v120, v174
	v_fmac_f32_e32 v86, v121, v174
	v_fmac_f32_e32 v32, v123, v174
	v_fmac_f32_e32 v74, v123, v173
	v_fma_f32 v39, v73, v173, v127
	v_fmac_f32_e32 v40, v77, v173
	v_fmac_f32_e32 v41, v98, v173
	v_fmac_f32_e32 v42, v99, v173
	v_fmac_f32_e32 v43, v100, v173
	v_fmac_f32_e32 v44, v101, v173
	v_fmac_f32_e32 v45, v102, v173
	v_fmac_f32_e32 v46, v103, v173
	v_fmac_f32_e32 v47, v104, v173
	v_fmac_f32_e32 v48, v105, v173
	v_fmac_f32_e32 v49, v106, v173
	v_fmac_f32_e32 v50, v107, v173
	v_fmac_f32_e32 v51, v108, v173
	v_fmac_f32_e32 v52, v109, v173
	v_fmac_f32_e32 v72, v110, v173
	v_fmac_f32_e32 v75, v111, v173
	v_fmac_f32_e32 v76, v112, v173
	v_fmac_f32_e32 v79, v113, v173
	v_pk_fma_f32 v[80:81], v[114:115], v[172:173], v[80:81] op_sel:[0,1,0] op_sel_hi:[1,1,1]
	v_pk_fma_f32 v[82:83], v[116:117], v[172:173], v[82:83] op_sel:[0,1,0] op_sel_hi:[1,1,1]
	v_fmac_f32_e32 v84, v118, v173
	v_fmac_f32_e32 v34, v119, v173
	v_fmac_f32_e32 v35, v120, v173
	v_fmac_f32_e32 v85, v121, v173
	v_fmac_f32_e32 v86, v122, v173
	v_fmac_f32_e32 v32, v124, v173
	v_fmac_f32_e32 v74, v124, v172
	v_and_b32_e32 v173, 64, v152
	v_fma_f32 v38, v73, v172, v127
	v_fmac_f32_e32 v39, v77, v172
	v_pk_fma_f32 v[40:41], v[98:99], v[172:173], v[40:41] op_sel_hi:[1,0,1]
	v_pk_fma_f32 v[42:43], v[100:101], v[172:173], v[42:43] op_sel_hi:[1,0,1]
	v_pk_fma_f32 v[44:45], v[102:103], v[172:173], v[44:45] op_sel_hi:[1,0,1]
	v_pk_fma_f32 v[46:47], v[104:105], v[172:173], v[46:47] op_sel_hi:[1,0,1]
	v_pk_fma_f32 v[48:49], v[106:107], v[172:173], v[48:49] op_sel_hi:[1,0,1]
	v_pk_fma_f32 v[50:51], v[108:109], v[172:173], v[50:51] op_sel_hi:[1,0,1]
	v_fmac_f32_e32 v52, v110, v172
	v_fmac_f32_e32 v72, v111, v172
	v_fmac_f32_e32 v75, v112, v172
	v_fmac_f32_e32 v76, v113, v172
	v_fmac_f32_e32 v79, v114, v172
	v_fmac_f32_e32 v80, v115, v172
	v_fmac_f32_e32 v81, v116, v172
	v_fmac_f32_e32 v82, v117, v172
	v_fmac_f32_e32 v83, v118, v172
	v_fmac_f32_e32 v84, v119, v172
	v_pk_fma_f32 v[34:35], v[120:121], v[172:173], v[34:35] op_sel_hi:[1,0,1]
	v_fmac_f32_e32 v85, v122, v172
	v_fmac_f32_e32 v86, v123, v172
	v_fmac_f32_e32 v32, v125, v172
	v_fmac_f32_e32 v74, v125, v171
	v_xor_b32_e32 v172, 32, v152
	v_add_u32_e32 v173, 64, v173
	v_fma_f32 v37, v73, v171, v127
	v_fmac_f32_e32 v38, v77, v171
	v_fmac_f32_e32 v39, v98, v171
	v_fmac_f32_e32 v40, v99, v171
	v_fmac_f32_e32 v41, v100, v171
	v_fmac_f32_e32 v42, v101, v171
	v_fmac_f32_e32 v43, v102, v171
	v_fmac_f32_e32 v44, v103, v171
	v_fmac_f32_e32 v45, v104, v171
	v_fmac_f32_e32 v46, v105, v171
	v_fmac_f32_e32 v47, v106, v171
	v_fmac_f32_e32 v48, v107, v171
	v_fmac_f32_e32 v49, v108, v171
	v_fmac_f32_e32 v50, v109, v171
	v_fmac_f32_e32 v51, v110, v171
	v_fmac_f32_e32 v52, v111, v171
	v_fmac_f32_e32 v72, v112, v171
	v_fmac_f32_e32 v75, v113, v171
	v_fmac_f32_e32 v76, v114, v171
	v_fmac_f32_e32 v79, v115, v171
	v_pk_fma_f32 v[80:81], v[116:117], v[170:171], v[80:81] op_sel:[0,1,0] op_sel_hi:[1,1,1]
	v_pk_fma_f32 v[82:83], v[118:119], v[170:171], v[82:83] op_sel:[0,1,0] op_sel_hi:[1,1,1]
	v_fmac_f32_e32 v84, v120, v171
	v_fmac_f32_e32 v34, v121, v171
	v_fmac_f32_e32 v35, v122, v171
	v_fmac_f32_e32 v85, v123, v171
	v_fmac_f32_e32 v86, v124, v171
	v_fmac_f32_e32 v32, v126, v171
	v_fmac_f32_e32 v74, v126, v170
	v_cmp_lt_i32_e32 vcc, v172, v173
	v_fma_f32 v36, v73, v170, v127
	v_fmac_f32_e32 v37, v77, v170
	v_pk_fma_f32 v[38:39], v[98:99], v[170:171], v[38:39] op_sel_hi:[1,0,1]
	v_pk_fma_f32 v[40:41], v[100:101], v[170:171], v[40:41] op_sel_hi:[1,0,1]
	v_pk_fma_f32 v[42:43], v[102:103], v[170:171], v[42:43] op_sel_hi:[1,0,1]
	v_pk_fma_f32 v[44:45], v[104:105], v[170:171], v[44:45] op_sel_hi:[1,0,1]
	v_pk_fma_f32 v[46:47], v[106:107], v[170:171], v[46:47] op_sel_hi:[1,0,1]
	v_pk_fma_f32 v[48:49], v[108:109], v[170:171], v[48:49] op_sel_hi:[1,0,1]
	v_pk_fma_f32 v[50:51], v[110:111], v[170:171], v[50:51] op_sel_hi:[1,0,1]
	v_fmac_f32_e32 v52, v112, v170
	v_fmac_f32_e32 v72, v113, v170
	v_fmac_f32_e32 v75, v114, v170
	v_fmac_f32_e32 v76, v115, v170
	v_fmac_f32_e32 v79, v116, v170
	v_fmac_f32_e32 v80, v117, v170
	v_fmac_f32_e32 v81, v118, v170
	v_fmac_f32_e32 v82, v119, v170
	v_fmac_f32_e32 v83, v120, v170
	v_fmac_f32_e32 v84, v121, v170
	v_pk_fma_f32 v[34:35], v[122:123], v[170:171], v[34:35] op_sel_hi:[1,0,1]
	v_fmac_f32_e32 v85, v124, v170
	v_fmac_f32_e32 v86, v125, v170
	v_mul_f32_e32 v170, v74, v74
	v_mul_f32_e32 v171, v32, v32
	v_cndmask_b32_e32 v172, v152, v172, vcc
	v_lshlrev_b32_e32 v172, 2, v172
	v_cndmask_b32_e64 v174, v32, v171, s[20:21]
	v_cndmask_b32_e64 v175, v74, v170, s[20:21]
	ds_bpermute_b32 v174, v172, v174
	ds_bpermute_b32 v175, v172, v175
	v_fmac_f32_e32 v35, v124, v169
	v_fmac_f32_e32 v36, v77, v169
	v_fmac_f32_e32 v37, v98, v169
	v_fmac_f32_e32 v38, v99, v169
	v_fmac_f32_e32 v39, v100, v169
	v_fmac_f32_e32 v40, v101, v169
	v_fmac_f32_e32 v41, v102, v169
	v_fmac_f32_e32 v42, v103, v169
	v_fmac_f32_e32 v43, v104, v169
	v_fmac_f32_e32 v44, v105, v169
	v_fmac_f32_e32 v45, v106, v169
	v_fmac_f32_e32 v46, v107, v169
	v_fmac_f32_e32 v47, v108, v169
	v_fmac_f32_e32 v48, v109, v169
	v_fmac_f32_e32 v49, v110, v169
	v_fmac_f32_e32 v50, v111, v169
	v_fmac_f32_e32 v51, v112, v169
	v_fmac_f32_e32 v52, v113, v169
	v_fmac_f32_e32 v72, v114, v169
	v_fmac_f32_e32 v75, v115, v169
	v_fmac_f32_e32 v76, v116, v169
	v_fmac_f32_e32 v79, v117, v169
	v_pk_fma_f32 v[80:81], v[118:119], v[168:169], v[80:81] op_sel:[0,1,0] op_sel_hi:[1,1,1]
	v_pk_fma_f32 v[82:83], v[120:121], v[168:169], v[82:83] op_sel:[0,1,0] op_sel_hi:[1,1,1]
	v_fmac_f32_e32 v84, v122, v169
	v_fmac_f32_e32 v34, v123, v169
	v_fmac_f32_e32 v85, v125, v169
	v_fmac_f32_e32 v35, v125, v168
	v_pk_fma_f32 v[36:37], v[98:99], v[168:169], v[36:37] op_sel_hi:[1,0,1]
	v_pk_fma_f32 v[38:39], v[100:101], v[168:169], v[38:39] op_sel_hi:[1,0,1]
	v_pk_fma_f32 v[40:41], v[102:103], v[168:169], v[40:41] op_sel_hi:[1,0,1]
	v_pk_fma_f32 v[42:43], v[104:105], v[168:169], v[42:43] op_sel_hi:[1,0,1]
	v_pk_fma_f32 v[44:45], v[106:107], v[168:169], v[44:45] op_sel_hi:[1,0,1]
	v_pk_fma_f32 v[46:47], v[108:109], v[168:169], v[46:47] op_sel_hi:[1,0,1]
	v_pk_fma_f32 v[48:49], v[110:111], v[168:169], v[48:49] op_sel_hi:[1,0,1]
	v_pk_fma_f32 v[50:51], v[112:113], v[168:169], v[50:51] op_sel_hi:[1,0,1]
	v_fmac_f32_e32 v52, v114, v168
	v_fmac_f32_e32 v72, v115, v168
	v_fmac_f32_e32 v75, v116, v168
	v_fmac_f32_e32 v76, v117, v168
	v_fmac_f32_e32 v79, v118, v168
	v_fmac_f32_e32 v80, v119, v168
	v_fmac_f32_e32 v81, v120, v168
	v_fmac_f32_e32 v82, v121, v168
	v_fmac_f32_e32 v83, v122, v168
	v_fmac_f32_e32 v84, v123, v168
	v_fmac_f32_e32 v34, v124, v168
	v_fmac_f32_e32 v86, v126, v169
	v_fmac_f32_e32 v85, v126, v168
	v_fmac_f32_e32 v35, v126, v167
	v_fmac_f32_e32 v36, v99, v167
	v_fmac_f32_e32 v37, v100, v167
	v_fmac_f32_e32 v38, v101, v167
	v_fmac_f32_e32 v39, v102, v167
	v_fmac_f32_e32 v40, v103, v167
	v_fmac_f32_e32 v41, v104, v167
	v_fmac_f32_e32 v42, v105, v167
	v_fmac_f32_e32 v43, v106, v167
	v_fmac_f32_e32 v44, v107, v167
	v_fmac_f32_e32 v45, v108, v167
	v_fmac_f32_e32 v46, v109, v167
	v_fmac_f32_e32 v47, v110, v167
	v_fmac_f32_e32 v48, v111, v167
	v_fmac_f32_e32 v49, v112, v167
	v_fmac_f32_e32 v50, v113, v167
	v_fmac_f32_e32 v51, v114, v167
	v_fmac_f32_e32 v52, v115, v167
	v_fmac_f32_e32 v72, v116, v167
	v_fmac_f32_e32 v75, v117, v167
	v_fmac_f32_e32 v76, v118, v167
	v_fmac_f32_e32 v79, v119, v167
	v_pk_fma_f32 v[80:81], v[120:121], v[166:167], v[80:81] op_sel:[0,1,0] op_sel_hi:[1,1,1]
	v_pk_fma_f32 v[82:83], v[122:123], v[166:167], v[82:83] op_sel:[0,1,0] op_sel_hi:[1,1,1]
	v_fmac_f32_e32 v84, v124, v167
	v_fmac_f32_e32 v34, v125, v167
	v_mul_f32_e32 v167, v35, v35
	v_mul_f32_e32 v168, v85, v85
	v_mul_f32_e32 v169, v86, v86
	v_cndmask_b32_e64 v171, v171, v32, s[20:21]
	v_cndmask_b32_e64 v170, v170, v74, s[20:21]
	v_cndmask_b32_e64 v176, v86, v169, s[20:21]
	s_waitcnt lgkmcnt(1)
	v_add_f32_e32 v171, v171, v174
	s_waitcnt lgkmcnt(0)
	v_add_f32_e32 v170, v170, v175
	v_cndmask_b32_e64 v174, v85, v168, s[20:21]
	v_cndmask_b32_e64 v175, v35, v167, s[20:21]
	ds_bpermute_b32 v176, v172, v176
	ds_bpermute_b32 v174, v172, v174
	ds_bpermute_b32 v175, v172, v175
	v_fmac_f32_e32 v83, v124, v166
	v_pk_fma_f32 v[36:37], v[100:101], v[166:167], v[36:37] op_sel_hi:[1,0,1]
	v_pk_fma_f32 v[38:39], v[102:103], v[166:167], v[38:39] op_sel_hi:[1,0,1]
	v_pk_fma_f32 v[40:41], v[104:105], v[166:167], v[40:41] op_sel_hi:[1,0,1]
	v_pk_fma_f32 v[42:43], v[106:107], v[166:167], v[42:43] op_sel_hi:[1,0,1]
	v_pk_fma_f32 v[44:45], v[108:109], v[166:167], v[44:45] op_sel_hi:[1,0,1]
	v_pk_fma_f32 v[46:47], v[110:111], v[166:167], v[46:47] op_sel_hi:[1,0,1]
	v_pk_fma_f32 v[48:49], v[112:113], v[166:167], v[48:49] op_sel_hi:[1,0,1]
	v_pk_fma_f32 v[50:51], v[114:115], v[166:167], v[50:51] op_sel_hi:[1,0,1]
	v_fmac_f32_e32 v52, v116, v166
	v_fmac_f32_e32 v72, v117, v166
	v_fmac_f32_e32 v75, v118, v166
	v_fmac_f32_e32 v76, v119, v166
	v_fmac_f32_e32 v79, v120, v166
	v_fmac_f32_e32 v80, v121, v166
	v_fmac_f32_e32 v81, v122, v166
	v_fmac_f32_e32 v82, v123, v166
	v_fmac_f32_e32 v84, v125, v166
	v_fmac_f32_e32 v83, v125, v165
	v_fmac_f32_e32 v36, v101, v165
	v_fmac_f32_e32 v37, v102, v165
	v_fmac_f32_e32 v38, v103, v165
	v_fmac_f32_e32 v39, v104, v165
	v_fmac_f32_e32 v40, v105, v165
	v_fmac_f32_e32 v41, v106, v165
	v_fmac_f32_e32 v42, v107, v165
	v_fmac_f32_e32 v43, v108, v165
	v_fmac_f32_e32 v44, v109, v165
	v_fmac_f32_e32 v45, v110, v165
	v_fmac_f32_e32 v46, v111, v165
	v_fmac_f32_e32 v47, v112, v165
	v_fmac_f32_e32 v48, v113, v165
	v_fmac_f32_e32 v49, v114, v165
	v_fmac_f32_e32 v50, v115, v165
	v_fmac_f32_e32 v51, v116, v165
	v_fmac_f32_e32 v52, v117, v165
	v_fmac_f32_e32 v72, v118, v165
	v_fmac_f32_e32 v75, v119, v165
	v_fmac_f32_e32 v76, v120, v165
	v_fmac_f32_e32 v79, v121, v165
	v_pk_fma_f32 v[80:81], v[122:123], v[164:165], v[80:81] op_sel:[0,1,0] op_sel_hi:[1,1,1]
	v_fmac_f32_e32 v82, v124, v165
	v_fmac_f32_e32 v34, v126, v166
	v_fmac_f32_e32 v84, v126, v165
	v_fmac_f32_e32 v83, v126, v164
	v_pk_fma_f32 v[36:37], v[102:103], v[164:165], v[36:37] op_sel_hi:[1,0,1]
	v_pk_fma_f32 v[38:39], v[104:105], v[164:165], v[38:39] op_sel_hi:[1,0,1]
	v_pk_fma_f32 v[40:41], v[106:107], v[164:165], v[40:41] op_sel_hi:[1,0,1]
	v_pk_fma_f32 v[42:43], v[108:109], v[164:165], v[42:43] op_sel_hi:[1,0,1]
	v_pk_fma_f32 v[44:45], v[110:111], v[164:165], v[44:45] op_sel_hi:[1,0,1]
	v_pk_fma_f32 v[46:47], v[112:113], v[164:165], v[46:47] op_sel_hi:[1,0,1]
	v_pk_fma_f32 v[48:49], v[114:115], v[164:165], v[48:49] op_sel_hi:[1,0,1]
	v_pk_fma_f32 v[50:51], v[116:117], v[164:165], v[50:51] op_sel_hi:[1,0,1]
	v_fmac_f32_e32 v52, v118, v164
	v_fmac_f32_e32 v72, v119, v164
	v_fmac_f32_e32 v75, v120, v164
	v_fmac_f32_e32 v76, v121, v164
	v_fmac_f32_e32 v79, v122, v164
	v_fmac_f32_e32 v80, v123, v164
	v_fmac_f32_e32 v81, v124, v164
	v_fmac_f32_e32 v82, v125, v164
	v_mul_f32_e32 v164, v83, v83
	v_mul_f32_e32 v165, v84, v84
	v_mul_f32_e32 v166, v34, v34
	v_cndmask_b32_e64 v169, v169, v86, s[20:21]
	v_cndmask_b32_e64 v168, v168, v85, s[20:21]
	v_cndmask_b32_e64 v167, v167, v35, s[20:21]
	s_waitcnt lgkmcnt(2)
	v_add_f32_e32 v169, v169, v176
	v_cndmask_b32_e64 v176, v34, v166, s[20:21]
	s_waitcnt lgkmcnt(1)
	v_add_f32_e32 v168, v168, v174
	s_waitcnt lgkmcnt(0)
	v_add_f32_e32 v167, v167, v175
	v_cndmask_b32_e64 v174, v84, v165, s[20:21]
	v_cndmask_b32_e64 v175, v83, v164, s[20:21]
	v_lshlrev_b32_e32 v163, 16, v87
	ds_bpermute_b32 v176, v172, v176
	ds_bpermute_b32 v174, v172, v174
	ds_bpermute_b32 v175, v172, v175
	v_lshlrev_b32_e32 v162, 16, v88
	v_fmac_f32_e32 v80, v124, v163
	v_lshlrev_b32_e32 v161, 16, v89
	v_fmac_f32_e32 v36, v103, v163
	v_fmac_f32_e32 v37, v104, v163
	v_fmac_f32_e32 v38, v105, v163
	v_fmac_f32_e32 v39, v106, v163
	v_fmac_f32_e32 v40, v107, v163
	v_fmac_f32_e32 v41, v108, v163
	v_fmac_f32_e32 v42, v109, v163
	v_fmac_f32_e32 v43, v110, v163
	v_fmac_f32_e32 v44, v111, v163
	v_fmac_f32_e32 v45, v112, v163
	v_fmac_f32_e32 v46, v113, v163
	v_fmac_f32_e32 v47, v114, v163
	v_fmac_f32_e32 v48, v115, v163
	v_fmac_f32_e32 v49, v116, v163
	v_fmac_f32_e32 v50, v117, v163
	v_fmac_f32_e32 v51, v118, v163
	v_fmac_f32_e32 v52, v119, v163
	v_fmac_f32_e32 v72, v120, v163
	v_fmac_f32_e32 v75, v121, v163
	v_fmac_f32_e32 v76, v122, v163
	v_fmac_f32_e32 v79, v123, v163
	v_fmac_f32_e32 v81, v125, v163
	v_fmac_f32_e32 v80, v125, v162
	v_pk_fma_f32 v[36:37], v[104:105], v[162:163], v[36:37] op_sel_hi:[1,0,1]
	v_pk_fma_f32 v[38:39], v[106:107], v[162:163], v[38:39] op_sel_hi:[1,0,1]
	v_pk_fma_f32 v[40:41], v[108:109], v[162:163], v[40:41] op_sel_hi:[1,0,1]
	v_pk_fma_f32 v[42:43], v[110:111], v[162:163], v[42:43] op_sel_hi:[1,0,1]
	v_pk_fma_f32 v[44:45], v[112:113], v[162:163], v[44:45] op_sel_hi:[1,0,1]
	v_pk_fma_f32 v[46:47], v[114:115], v[162:163], v[46:47] op_sel_hi:[1,0,1]
	v_pk_fma_f32 v[48:49], v[116:117], v[162:163], v[48:49] op_sel_hi:[1,0,1]
	v_pk_fma_f32 v[50:51], v[118:119], v[162:163], v[50:51] op_sel_hi:[1,0,1]
	v_fmac_f32_e32 v52, v120, v162
	v_fmac_f32_e32 v72, v121, v162
	v_fmac_f32_e32 v75, v122, v162
	v_fmac_f32_e32 v76, v123, v162
	v_fmac_f32_e32 v79, v124, v162
	v_fmac_f32_e32 v82, v126, v163
	v_fmac_f32_e32 v81, v126, v162
	v_fmac_f32_e32 v80, v126, v161
	v_fmac_f32_e32 v36, v105, v161
	v_fmac_f32_e32 v37, v106, v161
	v_fmac_f32_e32 v38, v107, v161
	v_fmac_f32_e32 v39, v108, v161
	v_fmac_f32_e32 v40, v109, v161
	v_fmac_f32_e32 v41, v110, v161
	v_fmac_f32_e32 v42, v111, v161
	v_fmac_f32_e32 v43, v112, v161
	v_fmac_f32_e32 v44, v113, v161
	v_fmac_f32_e32 v45, v114, v161
	v_fmac_f32_e32 v46, v115, v161
	v_fmac_f32_e32 v47, v116, v161
	v_fmac_f32_e32 v48, v117, v161
	v_fmac_f32_e32 v49, v118, v161
	v_fmac_f32_e32 v50, v119, v161
	v_fmac_f32_e32 v51, v120, v161
	v_fmac_f32_e32 v52, v121, v161
	v_fmac_f32_e32 v72, v122, v161
	v_fmac_f32_e32 v75, v123, v161
	v_fmac_f32_e32 v76, v124, v161
	v_fmac_f32_e32 v79, v125, v161
	v_mul_f32_e32 v161, v80, v80
	v_mul_f32_e32 v162, v81, v81
	v_mul_f32_e32 v163, v82, v82
	v_cndmask_b32_e64 v166, v166, v34, s[20:21]
	v_cndmask_b32_e64 v165, v165, v84, s[20:21]
	v_cndmask_b32_e64 v164, v164, v83, s[20:21]
	s_waitcnt lgkmcnt(2)
	v_add_f32_e32 v166, v166, v176
	v_cndmask_b32_e64 v176, v82, v163, s[20:21]
	s_waitcnt lgkmcnt(1)
	v_add_f32_e32 v165, v165, v174
	s_waitcnt lgkmcnt(0)
	v_add_f32_e32 v164, v164, v175
	v_cndmask_b32_e64 v174, v81, v162, s[20:21]
	v_cndmask_b32_e64 v175, v80, v161, s[20:21]
	v_lshlrev_b32_e32 v160, 16, v90
	ds_bpermute_b32 v176, v172, v176
	ds_bpermute_b32 v174, v172, v174
	ds_bpermute_b32 v175, v172, v175
	v_lshlrev_b32_e32 v159, 16, v91
	v_fmac_f32_e32 v75, v124, v160
	v_lshlrev_b32_e32 v158, 16, v92
	v_pk_fma_f32 v[36:37], v[106:107], v[160:161], v[36:37] op_sel_hi:[1,0,1]
	v_pk_fma_f32 v[38:39], v[108:109], v[160:161], v[38:39] op_sel_hi:[1,0,1]
	v_pk_fma_f32 v[40:41], v[110:111], v[160:161], v[40:41] op_sel_hi:[1,0,1]
	v_pk_fma_f32 v[42:43], v[112:113], v[160:161], v[42:43] op_sel_hi:[1,0,1]
	v_pk_fma_f32 v[44:45], v[114:115], v[160:161], v[44:45] op_sel_hi:[1,0,1]
	v_pk_fma_f32 v[46:47], v[116:117], v[160:161], v[46:47] op_sel_hi:[1,0,1]
	v_pk_fma_f32 v[48:49], v[118:119], v[160:161], v[48:49] op_sel_hi:[1,0,1]
	v_pk_fma_f32 v[50:51], v[120:121], v[160:161], v[50:51] op_sel_hi:[1,0,1]
	v_fmac_f32_e32 v52, v122, v160
	v_fmac_f32_e32 v72, v123, v160
	v_fmac_f32_e32 v76, v125, v160
	v_fmac_f32_e32 v75, v125, v159
	v_fmac_f32_e32 v36, v107, v159
	v_fmac_f32_e32 v37, v108, v159
	v_fmac_f32_e32 v38, v109, v159
	v_fmac_f32_e32 v39, v110, v159
	v_fmac_f32_e32 v40, v111, v159
	v_fmac_f32_e32 v41, v112, v159
	v_fmac_f32_e32 v42, v113, v159
	v_fmac_f32_e32 v43, v114, v159
	v_fmac_f32_e32 v44, v115, v159
	v_fmac_f32_e32 v45, v116, v159
	v_fmac_f32_e32 v46, v117, v159
	v_fmac_f32_e32 v47, v118, v159
	v_fmac_f32_e32 v48, v119, v159
	v_fmac_f32_e32 v49, v120, v159
	v_fmac_f32_e32 v50, v121, v159
	v_fmac_f32_e32 v51, v122, v159
	v_fmac_f32_e32 v52, v123, v159
	v_fmac_f32_e32 v72, v124, v159
	v_fmac_f32_e32 v79, v126, v160
	v_fmac_f32_e32 v76, v126, v159
	v_fmac_f32_e32 v75, v126, v158
	v_pk_fma_f32 v[36:37], v[108:109], v[158:159], v[36:37] op_sel_hi:[1,0,1]
	v_pk_fma_f32 v[38:39], v[110:111], v[158:159], v[38:39] op_sel_hi:[1,0,1]
	v_pk_fma_f32 v[40:41], v[112:113], v[158:159], v[40:41] op_sel_hi:[1,0,1]
	v_pk_fma_f32 v[42:43], v[114:115], v[158:159], v[42:43] op_sel_hi:[1,0,1]
	v_pk_fma_f32 v[44:45], v[116:117], v[158:159], v[44:45] op_sel_hi:[1,0,1]
	v_pk_fma_f32 v[46:47], v[118:119], v[158:159], v[46:47] op_sel_hi:[1,0,1]
	v_pk_fma_f32 v[48:49], v[120:121], v[158:159], v[48:49] op_sel_hi:[1,0,1]
	v_pk_fma_f32 v[50:51], v[122:123], v[158:159], v[50:51] op_sel_hi:[1,0,1]
	v_fmac_f32_e32 v52, v124, v158
	v_fmac_f32_e32 v72, v125, v158
	v_mul_f32_e32 v158, v75, v75
	v_mul_f32_e32 v159, v76, v76
	v_mul_f32_e32 v160, v79, v79
	v_cndmask_b32_e64 v163, v163, v82, s[20:21]
	v_cndmask_b32_e64 v162, v162, v81, s[20:21]
	v_cndmask_b32_e64 v161, v161, v80, s[20:21]
	s_waitcnt lgkmcnt(2)
	v_add_f32_e32 v163, v163, v176
	v_cndmask_b32_e64 v176, v79, v160, s[20:21]
	s_waitcnt lgkmcnt(1)
	v_add_f32_e32 v162, v162, v174
	s_waitcnt lgkmcnt(0)
	v_add_f32_e32 v161, v161, v175
	v_cndmask_b32_e64 v174, v76, v159, s[20:21]
	v_cndmask_b32_e64 v175, v75, v158, s[20:21]
	v_lshlrev_b32_e32 v157, 16, v93
	ds_bpermute_b32 v176, v172, v176
	ds_bpermute_b32 v174, v172, v174
	ds_bpermute_b32 v175, v172, v175
	v_lshlrev_b32_e32 v156, 16, v94
	v_fmac_f32_e32 v51, v124, v157
	v_lshlrev_b32_e32 v155, 16, v95
	v_fmac_f32_e32 v36, v109, v157
	v_fmac_f32_e32 v37, v110, v157
	v_fmac_f32_e32 v38, v111, v157
	v_fmac_f32_e32 v39, v112, v157
	v_fmac_f32_e32 v40, v113, v157
	v_fmac_f32_e32 v41, v114, v157
	v_fmac_f32_e32 v42, v115, v157
	v_fmac_f32_e32 v43, v116, v157
	v_fmac_f32_e32 v44, v117, v157
	v_fmac_f32_e32 v45, v118, v157
	v_fmac_f32_e32 v46, v119, v157
	v_fmac_f32_e32 v47, v120, v157
	v_fmac_f32_e32 v48, v121, v157
	v_fmac_f32_e32 v49, v122, v157
	v_fmac_f32_e32 v50, v123, v157
	v_fmac_f32_e32 v52, v125, v157
	v_fmac_f32_e32 v51, v125, v156
	v_pk_fma_f32 v[36:37], v[110:111], v[156:157], v[36:37] op_sel_hi:[1,0,1]
	v_pk_fma_f32 v[38:39], v[112:113], v[156:157], v[38:39] op_sel_hi:[1,0,1]
	v_pk_fma_f32 v[40:41], v[114:115], v[156:157], v[40:41] op_sel_hi:[1,0,1]
	v_pk_fma_f32 v[42:43], v[116:117], v[156:157], v[42:43] op_sel_hi:[1,0,1]
	v_pk_fma_f32 v[44:45], v[118:119], v[156:157], v[44:45] op_sel_hi:[1,0,1]
	v_pk_fma_f32 v[46:47], v[120:121], v[156:157], v[46:47] op_sel_hi:[1,0,1]
	v_pk_fma_f32 v[48:49], v[122:123], v[156:157], v[48:49] op_sel_hi:[1,0,1]
	v_fmac_f32_e32 v50, v124, v156
	v_fmac_f32_e32 v72, v126, v157
	v_fmac_f32_e32 v52, v126, v156
	v_fmac_f32_e32 v51, v126, v155
	v_fmac_f32_e32 v36, v111, v155
	v_fmac_f32_e32 v37, v112, v155
	v_fmac_f32_e32 v38, v113, v155
	v_fmac_f32_e32 v39, v114, v155
	v_fmac_f32_e32 v40, v115, v155
	v_fmac_f32_e32 v41, v116, v155
	v_fmac_f32_e32 v42, v117, v155
	v_fmac_f32_e32 v43, v118, v155
	v_fmac_f32_e32 v44, v119, v155
	v_fmac_f32_e32 v45, v120, v155
	v_fmac_f32_e32 v46, v121, v155
	v_fmac_f32_e32 v47, v122, v155
	v_fmac_f32_e32 v48, v123, v155
	v_fmac_f32_e32 v49, v124, v155
	v_fmac_f32_e32 v50, v125, v155
	v_mul_f32_e32 v155, v51, v51
	v_mul_f32_e32 v156, v52, v52
	v_mul_f32_e32 v157, v72, v72
	v_cndmask_b32_e64 v160, v160, v79, s[20:21]
	v_cndmask_b32_e64 v159, v159, v76, s[20:21]
	v_cndmask_b32_e64 v158, v158, v75, s[20:21]
	s_waitcnt lgkmcnt(2)
	v_add_f32_e32 v160, v160, v176
	v_cndmask_b32_e64 v176, v72, v157, s[20:21]
	s_waitcnt lgkmcnt(1)
	v_add_f32_e32 v159, v159, v174
	s_waitcnt lgkmcnt(0)
	v_add_f32_e32 v158, v158, v175
	v_cndmask_b32_e64 v174, v52, v156, s[20:21]
	v_cndmask_b32_e64 v175, v51, v155, s[20:21]
	v_lshlrev_b32_e32 v154, 16, v96
	ds_bpermute_b32 v176, v172, v176
	ds_bpermute_b32 v174, v172, v174
	ds_bpermute_b32 v175, v172, v175
	v_lshlrev_b32_e32 v153, 16, v97
	v_fmac_f32_e32 v48, v124, v154
	v_lshlrev_b32_e32 v97, 16, v194
	v_pk_fma_f32 v[36:37], v[112:113], v[154:155], v[36:37] op_sel_hi:[1,0,1]
	v_pk_fma_f32 v[38:39], v[114:115], v[154:155], v[38:39] op_sel_hi:[1,0,1]
	v_pk_fma_f32 v[40:41], v[116:117], v[154:155], v[40:41] op_sel_hi:[1,0,1]
	v_pk_fma_f32 v[42:43], v[118:119], v[154:155], v[42:43] op_sel_hi:[1,0,1]
	v_pk_fma_f32 v[44:45], v[120:121], v[154:155], v[44:45] op_sel_hi:[1,0,1]
	v_pk_fma_f32 v[46:47], v[122:123], v[154:155], v[46:47] op_sel_hi:[1,0,1]
	v_fmac_f32_e32 v49, v125, v154
	v_fmac_f32_e32 v48, v125, v153
	v_fmac_f32_e32 v36, v113, v153
	v_fmac_f32_e32 v37, v114, v153
	v_fmac_f32_e32 v38, v115, v153
	v_fmac_f32_e32 v39, v116, v153
	v_fmac_f32_e32 v40, v117, v153
	v_fmac_f32_e32 v41, v118, v153
	v_fmac_f32_e32 v42, v119, v153
	v_fmac_f32_e32 v43, v120, v153
	v_fmac_f32_e32 v44, v121, v153
	v_fmac_f32_e32 v45, v122, v153
	v_fmac_f32_e32 v46, v123, v153
	v_fmac_f32_e32 v47, v124, v153
	v_fmac_f32_e32 v50, v126, v154
	v_fmac_f32_e32 v49, v126, v153
	v_fmac_f32_e32 v48, v126, v97
	v_pk_fma_f32 v[36:37], v[114:115], v[96:97], v[36:37] op_sel:[0,1,0] op_sel_hi:[1,1,1]
	v_pk_fma_f32 v[38:39], v[116:117], v[96:97], v[38:39] op_sel:[0,1,0] op_sel_hi:[1,1,1]
	v_pk_fma_f32 v[40:41], v[118:119], v[96:97], v[40:41] op_sel:[0,1,0] op_sel_hi:[1,1,1]
	v_pk_fma_f32 v[42:43], v[120:121], v[96:97], v[42:43] op_sel:[0,1,0] op_sel_hi:[1,1,1]
	v_pk_fma_f32 v[44:45], v[122:123], v[96:97], v[44:45] op_sel:[0,1,0] op_sel_hi:[1,1,1]
	v_pk_fma_f32 v[46:47], v[124:125], v[96:97], v[46:47] op_sel:[0,1,0] op_sel_hi:[1,1,1]
	v_mul_f32_e32 v97, v48, v48
	v_mul_f32_e32 v153, v49, v49
	v_mul_f32_e32 v154, v50, v50
	v_cndmask_b32_e64 v157, v157, v72, s[20:21]
	v_cndmask_b32_e64 v156, v156, v52, s[20:21]
	v_cndmask_b32_e64 v155, v155, v51, s[20:21]
	s_waitcnt lgkmcnt(2)
	v_add_f32_e32 v157, v157, v176
	v_cndmask_b32_e64 v176, v50, v154, s[20:21]
	s_waitcnt lgkmcnt(1)
	v_add_f32_e32 v156, v156, v174
	s_waitcnt lgkmcnt(0)
	v_add_f32_e32 v155, v155, v175
	v_cndmask_b32_e64 v174, v49, v153, s[20:21]
	v_cndmask_b32_e64 v175, v48, v97, s[20:21]
	v_lshlrev_b32_e32 v96, 16, v195
	ds_bpermute_b32 v176, v172, v176
	ds_bpermute_b32 v174, v172, v174
	ds_bpermute_b32 v175, v172, v175
	v_lshlrev_b32_e32 v95, 16, v196
	v_fmac_f32_e32 v45, v124, v96
	v_lshlrev_b32_e32 v94, 16, v197
	v_fmac_f32_e32 v36, v115, v96
	v_fmac_f32_e32 v37, v116, v96
	v_fmac_f32_e32 v38, v117, v96
	v_fmac_f32_e32 v39, v118, v96
	v_fmac_f32_e32 v40, v119, v96
	v_fmac_f32_e32 v41, v120, v96
	v_fmac_f32_e32 v42, v121, v96
	v_fmac_f32_e32 v43, v122, v96
	v_fmac_f32_e32 v44, v123, v96
	v_fmac_f32_e32 v46, v125, v96
	v_fmac_f32_e32 v45, v125, v95
	v_pk_fma_f32 v[36:37], v[116:117], v[94:95], v[36:37] op_sel:[0,1,0] op_sel_hi:[1,1,1]
	v_pk_fma_f32 v[38:39], v[118:119], v[94:95], v[38:39] op_sel:[0,1,0] op_sel_hi:[1,1,1]
	v_pk_fma_f32 v[40:41], v[120:121], v[94:95], v[40:41] op_sel:[0,1,0] op_sel_hi:[1,1,1]
	v_pk_fma_f32 v[42:43], v[122:123], v[94:95], v[42:43] op_sel:[0,1,0] op_sel_hi:[1,1,1]
	v_fmac_f32_e32 v44, v124, v95
	v_fmac_f32_e32 v47, v126, v96
	v_fmac_f32_e32 v46, v126, v95
	v_fmac_f32_e32 v45, v126, v94
	v_fmac_f32_e32 v36, v117, v94
	v_fmac_f32_e32 v37, v118, v94
	v_fmac_f32_e32 v38, v119, v94
	v_fmac_f32_e32 v39, v120, v94
	v_fmac_f32_e32 v40, v121, v94
	v_fmac_f32_e32 v41, v122, v94
	v_fmac_f32_e32 v42, v123, v94
	v_fmac_f32_e32 v43, v124, v94
	v_fmac_f32_e32 v44, v125, v94
	v_mul_f32_e32 v94, v45, v45
	v_mul_f32_e32 v95, v46, v46
	v_mul_f32_e32 v96, v47, v47
	v_cndmask_b32_e64 v154, v154, v50, s[20:21]
	v_cndmask_b32_e64 v153, v153, v49, s[20:21]
	v_cndmask_b32_e64 v97, v97, v48, s[20:21]
	s_waitcnt lgkmcnt(2)
	v_add_f32_e32 v154, v154, v176
	v_cndmask_b32_e64 v176, v47, v96, s[20:21]
	s_waitcnt lgkmcnt(1)
	v_add_f32_e32 v153, v153, v174
	s_waitcnt lgkmcnt(0)
	v_add_f32_e32 v97, v97, v175
	v_cndmask_b32_e64 v174, v46, v95, s[20:21]
	v_cndmask_b32_e64 v175, v45, v94, s[20:21]
	v_lshlrev_b32_e32 v93, 16, v198
	ds_bpermute_b32 v176, v172, v176
	ds_bpermute_b32 v174, v172, v174
	ds_bpermute_b32 v175, v172, v175
	v_lshlrev_b32_e32 v92, 16, v199
	v_fmac_f32_e32 v42, v124, v93
	v_lshlrev_b32_e32 v91, 16, v200
	v_pk_fma_f32 v[36:37], v[118:119], v[92:93], v[36:37] op_sel:[0,1,0] op_sel_hi:[1,1,1]
	v_pk_fma_f32 v[38:39], v[120:121], v[92:93], v[38:39] op_sel:[0,1,0] op_sel_hi:[1,1,1]
	v_pk_fma_f32 v[40:41], v[122:123], v[92:93], v[40:41] op_sel:[0,1,0] op_sel_hi:[1,1,1]
	v_fmac_f32_e32 v43, v125, v93
	v_fmac_f32_e32 v42, v125, v92
	v_fmac_f32_e32 v36, v119, v92
	v_fmac_f32_e32 v37, v120, v92
	v_fmac_f32_e32 v38, v121, v92
	v_fmac_f32_e32 v39, v122, v92
	v_fmac_f32_e32 v40, v123, v92
	v_fmac_f32_e32 v41, v124, v92
	v_fmac_f32_e32 v44, v126, v93
	v_fmac_f32_e32 v43, v126, v92
	v_fmac_f32_e32 v42, v126, v91
	v_pk_fma_f32 v[36:37], v[120:121], v[90:91], v[36:37] op_sel:[0,1,0] op_sel_hi:[1,1,1]
	v_pk_fma_f32 v[38:39], v[122:123], v[90:91], v[38:39] op_sel:[0,1,0] op_sel_hi:[1,1,1]
	v_pk_fma_f32 v[40:41], v[124:125], v[90:91], v[40:41] op_sel:[0,1,0] op_sel_hi:[1,1,1]
	v_mul_f32_e32 v91, v42, v42
	v_mul_f32_e32 v92, v43, v43
	v_mul_f32_e32 v93, v44, v44
	v_cndmask_b32_e64 v96, v96, v47, s[20:21]
	v_cndmask_b32_e64 v95, v95, v46, s[20:21]
	v_cndmask_b32_e64 v94, v94, v45, s[20:21]
	s_waitcnt lgkmcnt(2)
	v_add_f32_e32 v96, v96, v176
	v_cndmask_b32_e64 v176, v44, v93, s[20:21]
	s_waitcnt lgkmcnt(1)
	v_add_f32_e32 v95, v95, v174
	s_waitcnt lgkmcnt(0)
	v_add_f32_e32 v94, v94, v175
	v_cndmask_b32_e64 v174, v43, v92, s[20:21]
	v_cndmask_b32_e64 v175, v42, v91, s[20:21]
	v_lshlrev_b32_e32 v90, 16, v201
	ds_bpermute_b32 v176, v172, v176
	ds_bpermute_b32 v174, v172, v174
	ds_bpermute_b32 v175, v172, v175
	v_lshlrev_b32_e32 v89, 16, v202
	v_fmac_f32_e32 v39, v124, v90
	v_lshlrev_b32_e32 v88, 16, v203
	v_fmac_f32_e32 v36, v121, v90
	v_fmac_f32_e32 v37, v122, v90
	v_fmac_f32_e32 v38, v123, v90
	v_fmac_f32_e32 v40, v125, v90
	v_fmac_f32_e32 v39, v125, v89
	v_pk_fma_f32 v[36:37], v[122:123], v[88:89], v[36:37] op_sel:[0,1,0] op_sel_hi:[1,1,1]
	v_fmac_f32_e32 v38, v124, v89
	v_fmac_f32_e32 v41, v126, v90
	v_fmac_f32_e32 v40, v126, v89
	v_fmac_f32_e32 v39, v126, v88
	v_fmac_f32_e32 v36, v123, v88
	v_fmac_f32_e32 v37, v124, v88
	v_fmac_f32_e32 v38, v125, v88
	v_mul_f32_e32 v88, v39, v39
	v_mul_f32_e32 v89, v40, v40
	v_mul_f32_e32 v90, v41, v41
	v_cndmask_b32_e64 v93, v93, v44, s[20:21]
	v_cndmask_b32_e64 v92, v92, v43, s[20:21]
	v_cndmask_b32_e64 v91, v91, v42, s[20:21]
	s_waitcnt lgkmcnt(2)
	v_add_f32_e32 v93, v93, v176
	v_cndmask_b32_e64 v176, v41, v90, s[20:21]
	s_waitcnt lgkmcnt(1)
	v_add_f32_e32 v92, v92, v174
	s_waitcnt lgkmcnt(0)
	v_add_f32_e32 v91, v91, v175
	v_cndmask_b32_e64 v174, v40, v89, s[20:21]
	v_cndmask_b32_e64 v175, v39, v88, s[20:21]
	v_lshlrev_b32_e32 v87, 16, v204
	ds_bpermute_b32 v176, v172, v176
	ds_bpermute_b32 v174, v172, v174
	ds_bpermute_b32 v175, v172, v175
	v_lshlrev_b32_e32 v78, 16, v205
	v_fmac_f32_e32 v36, v124, v87
	v_lshlrev_b32_e32 v33, 16, v206
	v_fmac_f32_e32 v37, v125, v87
	v_fmac_f32_e32 v36, v125, v78
	v_fmac_f32_e32 v38, v126, v87
	v_fmac_f32_e32 v37, v126, v78
	v_fmac_f32_e32 v36, v126, v33
	v_mul_f32_e32 v33, v36, v36
	v_mul_f32_e32 v78, v37, v37
	v_mul_f32_e32 v87, v38, v38
	v_cndmask_b32_e64 v90, v90, v41, s[20:21]
	v_cndmask_b32_e64 v89, v89, v40, s[20:21]
	v_cndmask_b32_e64 v88, v88, v39, s[20:21]
	s_waitcnt lgkmcnt(2)
	v_add_f32_e32 v90, v90, v176
	v_cndmask_b32_e64 v176, v38, v87, s[20:21]
	s_waitcnt lgkmcnt(1)
	v_add_f32_e32 v89, v89, v174
	s_waitcnt lgkmcnt(0)
	v_add_f32_e32 v88, v88, v175
	v_cndmask_b32_e64 v174, v37, v78, s[20:21]
	v_cndmask_b32_e64 v175, v36, v33, s[20:21]
	ds_bpermute_b32 v176, v172, v176
	ds_bpermute_b32 v174, v172, v174
	ds_bpermute_b32 v172, v172, v175
	v_xor_b32_e32 v175, 16, v152
	v_cmp_lt_i32_e32 vcc, v175, v173
	v_cndmask_b32_e64 v87, v87, v38, s[20:21]
	v_cndmask_b32_e64 v33, v33, v36, s[20:21]
	v_cndmask_b32_e32 v175, v152, v175, vcc
	s_waitcnt lgkmcnt(2)
	v_add_f32_e32 v87, v87, v176
	v_lshlrev_b32_e32 v175, 2, v175
	v_cndmask_b32_e64 v176, v171, v155, s[22:23]
	s_waitcnt lgkmcnt(0)
	v_add_f32_e32 v33, v33, v172
	v_cndmask_b32_e64 v155, v155, v171, s[22:23]
	v_cndmask_b32_e64 v171, v170, v154, s[22:23]
	v_cndmask_b32_e64 v172, v168, v97, s[22:23]
	v_cndmask_b32_e64 v97, v97, v168, s[22:23]
	v_cndmask_b32_e64 v168, v167, v96, s[22:23]
	v_cndmask_b32_e64 v78, v78, v37, s[20:21]
	v_cndmask_b32_e64 v154, v154, v170, s[22:23]
	ds_bpermute_b32 v170, v175, v171
	v_cndmask_b32_e64 v171, v169, v153, s[22:23]
	v_cndmask_b32_e64 v153, v153, v169, s[22:23]
	v_cndmask_b32_e64 v96, v96, v167, s[22:23]
	ds_bpermute_b32 v167, v175, v168
	v_cndmask_b32_e64 v168, v166, v95, s[22:23]
	v_cndmask_b32_e64 v169, v165, v94, s[22:23]
	v_cndmask_b32_e64 v95, v95, v166, s[22:23]
	v_cndmask_b32_e64 v94, v94, v165, s[22:23]
	v_cndmask_b32_e64 v165, v164, v93, s[22:23]
	v_cndmask_b32_e64 v166, v162, v91, s[22:23]
	v_cndmask_b32_e64 v91, v91, v162, s[22:23]
	v_cndmask_b32_e64 v162, v161, v90, s[22:23]
	v_add_f32_e32 v78, v78, v174
	v_cndmask_b32_e64 v93, v93, v164, s[22:23]
	ds_bpermute_b32 v164, v175, v165
	v_cndmask_b32_e64 v165, v163, v92, s[22:23]
	v_cndmask_b32_e64 v92, v92, v163, s[22:23]
	v_cndmask_b32_e64 v90, v90, v161, s[22:23]
	ds_bpermute_b32 v161, v175, v162
	v_cndmask_b32_e64 v162, v160, v89, s[22:23]
	v_cndmask_b32_e64 v163, v159, v88, s[22:23]
	v_cndmask_b32_e64 v88, v88, v159, s[22:23]
	v_cndmask_b32_e64 v159, v158, v87, s[22:23]
	ds_bpermute_b32 v176, v175, v176
	ds_bpermute_b32 v171, v175, v171
	ds_bpermute_b32 v172, v175, v172
	ds_bpermute_b32 v165, v175, v165
	ds_bpermute_b32 v162, v175, v162
	v_cndmask_b32_e64 v87, v87, v158, s[22:23]
	ds_bpermute_b32 v158, v175, v159
	v_cndmask_b32_e64 v159, v157, v78, s[22:23]
	ds_bpermute_b32 v168, v175, v168
	ds_bpermute_b32 v169, v175, v169
	ds_bpermute_b32 v166, v175, v166
	ds_bpermute_b32 v163, v175, v163
	v_cndmask_b32_e64 v89, v89, v160, s[22:23]
	ds_bpermute_b32 v159, v175, v159
	v_cndmask_b32_e64 v160, v156, v33, s[22:23]
	ds_bpermute_b32 v160, v175, v160
	v_cndmask_b32_e64 v33, v33, v156, s[22:23]
	v_xor_b32_e32 v156, 8, v152
	v_cmp_lt_i32_e32 vcc, v156, v173
	s_waitcnt lgkmcnt(11)
	v_add_f32_e32 v155, v155, v176
	s_waitcnt lgkmcnt(10)
	v_add_f32_e32 v153, v153, v171
	s_waitcnt lgkmcnt(9)
	v_add_f32_e32 v97, v97, v172
	s_waitcnt lgkmcnt(8)
	v_add_f32_e32 v92, v92, v165
	v_add_f32_e32 v90, v90, v161
	s_waitcnt lgkmcnt(7)
	v_add_f32_e32 v89, v89, v162
	v_cndmask_b32_e64 v78, v78, v157, s[22:23]
	v_cndmask_b32_e32 v156, v152, v156, vcc
	v_add_f32_e32 v154, v154, v170
	v_add_f32_e32 v96, v96, v167
	s_waitcnt lgkmcnt(5)
	v_add_f32_e32 v95, v95, v168
	s_waitcnt lgkmcnt(4)
	v_add_f32_e32 v94, v94, v169
	s_waitcnt lgkmcnt(3)
	v_add_f32_e32 v91, v91, v166
	s_waitcnt lgkmcnt(2)
	v_add_f32_e32 v88, v88, v163
	v_add_f32_e32 v87, v87, v158
	s_waitcnt lgkmcnt(1)
	v_add_f32_e32 v78, v78, v159
	v_lshlrev_b32_e32 v156, 2, v156
	v_cndmask_b32_e64 v157, v155, v92, s[24:25]
	v_cndmask_b32_e64 v158, v153, v90, s[24:25]
	v_cndmask_b32_e64 v90, v90, v153, s[24:25]
	v_cndmask_b32_e64 v153, v97, v89, s[24:25]
	v_add_f32_e32 v93, v93, v164
	s_waitcnt lgkmcnt(0)
	v_add_f32_e32 v33, v33, v160
	v_cndmask_b32_e64 v92, v92, v155, s[24:25]
	ds_bpermute_b32 v155, v156, v157
	v_cndmask_b32_e64 v157, v154, v91, s[24:25]
	v_cndmask_b32_e64 v91, v91, v154, s[24:25]
	v_cndmask_b32_e64 v89, v89, v97, s[24:25]
	ds_bpermute_b32 v97, v156, v153
	v_cndmask_b32_e64 v153, v96, v88, s[24:25]
	v_cndmask_b32_e64 v154, v95, v87, s[24:25]
	v_cndmask_b32_e64 v87, v87, v95, s[24:25]
	v_cndmask_b32_e64 v95, v94, v78, s[24:25]
	ds_bpermute_b32 v157, v156, v157
	ds_bpermute_b32 v153, v156, v153
	ds_bpermute_b32 v154, v156, v154
	v_cndmask_b32_e64 v78, v78, v94, s[24:25]
	ds_bpermute_b32 v94, v156, v95
	v_cndmask_b32_e64 v95, v93, v33, s[24:25]
	ds_bpermute_b32 v158, v156, v158
	ds_bpermute_b32 v95, v156, v95
	v_cndmask_b32_e64 v88, v88, v96, s[24:25]
	v_xor_b32_e32 v96, 4, v152
	v_cmp_lt_i32_e32 vcc, v96, v173
	s_waitcnt lgkmcnt(7)
	v_add_f32_e32 v92, v92, v155
	s_waitcnt lgkmcnt(5)
	v_add_f32_e32 v91, v91, v157
	s_waitcnt lgkmcnt(4)
	v_add_f32_e32 v88, v88, v153
	s_waitcnt lgkmcnt(3)
	v_add_f32_e32 v87, v87, v154
	v_cndmask_b32_e32 v96, v152, v96, vcc
	v_cndmask_b32_e64 v33, v33, v93, s[24:25]
	s_waitcnt lgkmcnt(1)
	v_add_f32_e32 v90, v90, v158
	v_add_f32_e32 v89, v89, v97
	v_lshlrev_b32_e32 v96, 2, v96
	v_cndmask_b32_e64 v97, v92, v88, s[26:27]
	v_add_f32_e32 v78, v78, v94
	s_waitcnt lgkmcnt(0)
	v_add_f32_e32 v33, v33, v95
	v_cndmask_b32_e64 v88, v88, v92, s[26:27]
	v_cndmask_b32_e64 v92, v91, v87, s[26:27]
	v_cndmask_b32_e64 v87, v87, v91, s[26:27]
	ds_bpermute_b32 v91, v96, v92
	v_cndmask_b32_e64 v92, v90, v78, s[26:27]
	v_cndmask_b32_e64 v93, v89, v33, s[26:27]
	ds_bpermute_b32 v97, v96, v97
	ds_bpermute_b32 v92, v96, v92
	ds_bpermute_b32 v93, v96, v93
	v_cndmask_b32_e64 v33, v33, v89, s[26:27]
	v_xor_b32_e32 v89, 2, v152
	v_cndmask_b32_e64 v78, v78, v90, s[26:27]
	v_cmp_lt_i32_e32 vcc, v89, v173
	s_waitcnt lgkmcnt(2)
	v_add_f32_e32 v88, v88, v97
	v_add_f32_e32 v87, v87, v91
	s_waitcnt lgkmcnt(1)
	v_add_f32_e32 v78, v78, v92
	s_waitcnt lgkmcnt(0)
	v_add_f32_e32 v33, v33, v93
	v_cndmask_b32_e32 v89, v152, v89, vcc
	v_lshlrev_b32_e32 v89, 2, v89
	v_cndmask_b32_e64 v90, v88, v78, s[28:29]
	v_cndmask_b32_e64 v91, v87, v33, s[28:29]
	ds_bpermute_b32 v90, v89, v90
	ds_bpermute_b32 v89, v89, v91
	v_cndmask_b32_e64 v33, v33, v87, s[28:29]
	v_xor_b32_e32 v87, 1, v152
	v_cndmask_b32_e64 v78, v78, v88, s[28:29]
	v_cmp_lt_i32_e32 vcc, v87, v173
	s_waitcnt lgkmcnt(1)
	v_add_f32_e32 v78, v78, v90
	s_waitcnt lgkmcnt(0)
	v_add_f32_e32 v33, v33, v89
	v_cndmask_b32_e32 v87, v152, v87, vcc
	v_lshlrev_b32_e32 v87, 2, v87
	v_cndmask_b32_e64 v88, v78, v33, s[30:31]
	ds_bpermute_b32 v87, v87, v88
	v_cndmask_b32_e64 v33, v33, v78, s[30:31]
	s_waitcnt lgkmcnt(0)
	s_barrier
	v_add_f32_e32 v33, v33, v87
	ds_write_b32 v144, v33
	s_waitcnt lgkmcnt(0)
	s_barrier
	s_mov_b64 s[76:77], exec
	v_readlane_b32 s4, v255, 20
	v_readlane_b32 s5, v255, 21
	s_and_b64 s[4:5], s[76:77], s[4:5]
	s_mov_b64 exec, s[4:5]
	s_cbranch_execz .LBB0_502
	ds_read2st64_b32 v[88:89], v144 offset1:1
	s_waitcnt lgkmcnt(0)
	v_add_f32_e32 v33, 0, v88
	v_add_f32_e32 v33, v33, v89
	ds_read2st64_b32 v[88:89], v144 offset0:2 offset1:3
	s_waitcnt lgkmcnt(0)
	v_add_f32_e32 v33, v33, v88
	v_add_f32_e32 v33, v33, v89
	ds_read2st64_b32 v[88:89], v144 offset0:4 offset1:5
	s_waitcnt lgkmcnt(0)
	v_add_f32_e32 v33, v33, v88
	v_add_f32_e32 v33, v33, v89
	ds_read2st64_b32 v[88:89], v144 offset0:6 offset1:7
	s_waitcnt lgkmcnt(0)
	v_add_f32_e32 v33, v33, v88
	v_add_f32_e32 v33, v33, v89
	ds_write_b32 v144, v33 offset:2048
	s_branch .LBB0_502
